# NA attention: K re-fragment LDS reads issued ahead of the V-tile LDS writes so their latency overlaps the V load waits
# speedup vs baseline: 1.0011x; 1.0011x over previous
.LBB0_611:
	s_waitcnt vmcnt(12)
	ds_write_b128 v184, v[64:67] offset:46080
	ds_write_b128 v184, v[68:71] offset:47232
	ds_write_b128 v184, v[72:75] offset:48384
	ds_write_b128 v184, v[76:79] offset:49536
	s_waitcnt lgkmcnt(0)
	ds_read_b128 v[64:67], v185 offset:46080
	ds_read_b128 v[68:71], v185 offset:46112
	ds_read_b128 v[72:75], v185 offset:46144
	ds_read_b128 v[76:79], v185 offset:46176
	s_add_i32 s81, s93, 14
	s_add_i32 s33, s93, 16
	s_cmp_ge_u32 s33, s84
	s_waitcnt vmcnt(11)
	ds_write_b128 v184, v[80:83]
	s_waitcnt vmcnt(8)
	ds_write_b128 v184, v[92:95] offset:1152
	ds_write_b128 v184, v[88:91] offset:2304
	ds_write_b128 v184, v[84:87] offset:3456
	s_waitcnt lgkmcnt(4)
	v_mfma_f32_32x32x16_bf16 v[32:47], v[64:67], v[48:51], 0
	v_mfma_f32_32x32x16_bf16 v[32:47], v[68:71], v[52:55], v[32:47]
	v_mfma_f32_32x32x16_bf16 v[32:47], v[72:75], v[56:59], v[32:47]
	v_mfma_f32_32x32x16_bf16 v[32:47], v[76:79], v[60:63], v[32:47]
	s_cbranch_scc1 .LBB0_617
	s_cmp_lt_u32 s81, 14
	s_cselect_b64 s[0:1], -1, 0
	s_and_b64 s[0:1], s[76:77], s[0:1]
	s_andn2_b64 vcc, exec, s[0:1]
	s_mov_b64 s[0:1], -1
	s_cbranch_vccz .LBB0_614
	s_and_b64 s[0:1], s[76:77], exec
	s_cselect_b32 s0, s93, s33
	s_lshl_b32 s0, s0, 5
	s_add_i32 s68, s0, s86
	s_mov_b64 s[0:1], 0

.LBB0_619:
	s_nop 3
	v_max_f32_e32 v222, v33, v33
	v_max_f32_e32 v223, v32, v32
	v_max_f32_e32 v222, v223, v222
	v_max3_f32 v222, v222, v34, v35
	v_max3_f32 v222, v222, v36, v37
	v_max3_f32 v222, v222, v38, v39
	v_max3_f32 v222, v222, v40, v41
	v_max3_f32 v222, v222, v42, v43
	v_max3_f32 v222, v222, v44, v45
	v_max3_f32 v222, v222, v46, v47
	ds_bpermute_b32 v223, v169, v222
	s_waitcnt lgkmcnt(0)
	s_add_i32 s0, s93, 17
	s_cmp_ge_u32 s0, s84
	s_waitcnt lgkmcnt(0)
	v_max3_f32 v233, v140, v222, v223
	v_sub_f32_e32 v32, v32, v233
	v_exp_f32_e32 v234, v32
	v_sub_f32_e32 v32, v33, v233
	v_exp_f32_e32 v235, v32
	v_sub_f32_e32 v32, v34, v233
	v_exp_f32_e32 v236, v32
	v_sub_f32_e32 v32, v35, v233
	v_exp_f32_e32 v237, v32
	v_sub_f32_e32 v32, v36, v233
	v_exp_f32_e32 v238, v32
	v_sub_f32_e32 v32, v37, v233
	v_exp_f32_e32 v239, v32
	v_sub_f32_e32 v32, v38, v233
	v_exp_f32_e32 v240, v32
	v_sub_f32_e32 v32, v39, v233
	v_exp_f32_e32 v241, v32
	v_sub_f32_e32 v32, v40, v233
	v_exp_f32_e32 v242, v32
	v_sub_f32_e32 v32, v41, v233
	v_exp_f32_e32 v243, v32
	v_sub_f32_e32 v32, v42, v233
	v_exp_f32_e32 v244, v32
	v_sub_f32_e32 v32, v43, v233
	ds_read_b64_tr_b16 v[36:37], v229
	ds_read_b64_tr_b16 v[38:39], v229 offset:1152
	v_sub_f32_e32 v140, v140, v233
	v_exp_f32_e32 v245, v32
	v_sub_f32_e32 v32, v44, v233
	v_exp_f32_e32 v140, v140
	s_waitcnt lgkmcnt(2)
	s_waitcnt lgkmcnt(0)
	v_exp_f32_e32 v246, v32
	v_sub_f32_e32 v32, v45, v233
	v_exp_f32_e32 v247, v32
	v_sub_f32_e32 v32, v46, v233
	v_exp_f32_e32 v248, v32
	v_sub_f32_e32 v32, v47, v233
	v_exp_f32_e32 v249, v32
	v_cvt_pk_bf16_f32 v32, v234, v235
	v_cvt_pk_bf16_f32 v33, v236, v237
	v_cvt_pk_bf16_f32 v34, v238, v239
	v_cvt_pk_bf16_f32 v35, v240, v241
	v_pk_mul_f32 v[30:31], v[30:31], v[140:141] op_sel_hi:[1,0]
	v_pk_mul_f32 v[28:29], v[28:29], v[140:141] op_sel_hi:[1,0]
	v_pk_mul_f32 v[26:27], v[26:27], v[140:141] op_sel_hi:[1,0]
	v_pk_mul_f32 v[24:25], v[24:25], v[140:141] op_sel_hi:[1,0]
	v_pk_mul_f32 v[22:23], v[22:23], v[140:141] op_sel_hi:[1,0]
	v_pk_mul_f32 v[20:21], v[20:21], v[140:141] op_sel_hi:[1,0]
	v_pk_mul_f32 v[18:19], v[18:19], v[140:141] op_sel_hi:[1,0]
	v_pk_mul_f32 v[16:17], v[16:17], v[140:141] op_sel_hi:[1,0]
	v_pk_mul_f32 v[14:15], v[14:15], v[140:141] op_sel_hi:[1,0]
	v_pk_mul_f32 v[12:13], v[12:13], v[140:141] op_sel_hi:[1,0]
	v_mfma_f32_32x32x16_bf16 v[16:31], v[36:39], v[32:35], v[16:31]
	ds_read_b64_tr_b16 v[36:37], v229 offset:64
	ds_read_b64_tr_b16 v[38:39], v229 offset:1216
	s_waitcnt lgkmcnt(2)
	v_pk_mul_f32 v[10:11], v[10:11], v[140:141] op_sel_hi:[1,0]
	s_waitcnt lgkmcnt(0)
	v_pk_mul_f32 v[8:9], v[8:9], v[140:141] op_sel_hi:[1,0]
	v_pk_mul_f32 v[6:7], v[6:7], v[140:141] op_sel_hi:[1,0]
	v_pk_mul_f32 v[4:5], v[4:5], v[140:141] op_sel_hi:[1,0]
	v_pk_mul_f32 v[2:3], v[2:3], v[140:141] op_sel_hi:[1,0]
	v_pk_mul_f32 v[0:1], v[0:1], v[140:141] op_sel_hi:[1,0]
	s_nop 1
	v_mfma_f32_32x32x16_bf16 v[0:15], v[36:39], v[32:35], v[0:15]
	ds_read_b64_tr_b16 v[36:37], v229 offset:2304
	ds_read_b64_tr_b16 v[38:39], v229 offset:3456
	s_waitcnt lgkmcnt(2)
	v_cvt_pk_bf16_f32 v32, v242, v243
	s_waitcnt lgkmcnt(0)
	v_cvt_pk_bf16_f32 v33, v244, v245
	v_cvt_pk_bf16_f32 v34, v246, v247
	v_cvt_pk_bf16_f32 v35, v248, v249
	s_nop 1
	v_mfma_f32_32x32x16_bf16 v[16:31], v[36:39], v[32:35], v[16:31]
	ds_read_b64_tr_b16 v[36:37], v229 offset:2368
	ds_read_b64_tr_b16 v[38:39], v229 offset:3520
	s_waitcnt lgkmcnt(2)
	s_waitcnt lgkmcnt(0)
	s_waitcnt vmcnt(3)
	ds_write_b128 v184, v[96:99] offset:46080
	ds_write_b128 v184, v[100:103] offset:47232
	ds_write_b128 v184, v[104:107] offset:48384
	ds_write_b128 v184, v[108:111] offset:49536
	s_waitcnt lgkmcnt(0)
	ds_read_b128 v[96:99], v185 offset:46080
	ds_read_b128 v[100:103], v185 offset:46112
	ds_read_b128 v[104:107], v185 offset:46144
	ds_read_b128 v[108:111], v185 offset:46176
	ds_write_b128 v184, v[112:115]
	s_waitcnt vmcnt(0)
	ds_write_b128 v184, v[124:127] offset:1152
	ds_write_b128 v184, v[120:123] offset:2304
	ds_write_b128 v184, v[116:119] offset:3456
	v_mfma_f32_32x32x16_bf16 v[0:15], v[36:39], v[32:35], v[0:15]
	s_waitcnt lgkmcnt(4)
	v_mfma_f32_32x32x16_bf16 v[32:47], v[96:99], v[48:51], 0
	v_mfma_f32_32x32x16_bf16 v[32:47], v[100:103], v[52:55], v[32:47]
	v_mfma_f32_32x32x16_bf16 v[32:47], v[104:107], v[56:59], v[32:47]
	v_mfma_f32_32x32x16_bf16 v[32:47], v[108:111], v[60:63], v[32:47]
	s_cbranch_scc1 .LBB0_623
	s_cmp_lt_u32 s81, 13
	s_cselect_b64 vcc, -1, 0
	s_and_b64 vcc, s[76:77], vcc
	s_and_b64 vcc, exec, vcc
	s_mov_b32 s1, s87
	s_cbranch_vccnz .LBB0_622
	s_add_i32 s1, s93, 1
	s_and_b64 vcc, s[76:77], exec
	s_cselect_b32 s0, s1, s0
	s_lshl_b32 s0, s0, 5
	s_add_i32 s1, s0, s86
